# seams after P1, conv, P4, fixup (phases whose stores are all sc1 write-through, drained by vmcnt(0) before arrival): XCD leader's buffer_wbl2 dropped from the grid barrier
# speedup vs baseline: 1.0067x; 1.0067x over previous
; __device__ __forceinline__ unsigned xb_add(unsigned* p, unsigned v) { return __hip_atomic_fetch_add(p, v, __ATOMIC_RELAXED, __HIP_MEMORY_SCOPE_AGENT); }
; __device__ __forceinline__ void xcd_barrier(const XcdBarrier& b) {
;     ...
;         const unsigned old = xb_add(&bar[XB_XSUB(b.x)], 1u);
;         const unsigned gen = old / nloc;
;         if (old + 1u == (gen + 1u) * nloc) {
;             __builtin_amdgcn_fence(__ATOMIC_RELEASE, "agent");
;             asm volatile("s_waitcnt vmcnt(0)" ::: "memory");
;             const unsigned og = xb_add(&bar[XB_TOP], 1u);
;             const unsigned tg = og / nx;
;             if (og + 1u == (tg + 1u) * nx) xb_add(&bar[XB_TOPGEN], 1u);
.LBB0_154:
	s_andn2_saveexec_b64 s[6:7], s[6:7]
	s_cbranch_execz .LBB0_172
	s_mov_b64 s[6:7], exec
	s_waitcnt lgkmcnt(0)
	s_waitcnt vmcnt(0)
	v_mbcnt_lo_u32_b32 v1, s6, 0
	v_mbcnt_hi_u32_b32 v1, s7, v1
	v_cmp_eq_u32_e32 vcc, 0, v1
	s_and_saveexec_b64 s[8:9], vcc
	s_cbranch_execz .LBB0_157
	s_bcnt1_i32_b64 s6, s[6:7]
	v_mov_b32_e32 v2, 0xffc3000
	v_mov_b32_e32 v3, s6
	global_atomic_add v2, v2, v3, s[88:89] offset:1024 sc0

; __device__ __forceinline__ unsigned xb_add(unsigned* p, unsigned v) { return __hip_atomic_fetch_add(p, v, __ATOMIC_RELAXED, __HIP_MEMORY_SCOPE_AGENT); }
; __device__ __forceinline__ void xcd_barrier(const XcdBarrier& b) {
;     ...
;         const unsigned old = xb_add(&bar[XB_XSUB(b.x)], 1u);
;         const unsigned gen = old / nloc;
;         if (old + 1u == (gen + 1u) * nloc) {
;             __builtin_amdgcn_fence(__ATOMIC_RELEASE, "agent");
;             asm volatile("s_waitcnt vmcnt(0)" ::: "memory");
;             const unsigned og = xb_add(&bar[XB_TOP], 1u);
;             const unsigned tg = og / nx;
;             if (og + 1u == (tg + 1u) * nx) xb_add(&bar[XB_TOPGEN], 1u);
.LBB0_734:
	s_andn2_saveexec_b64 s[8:9], s[8:9]
	s_cbranch_execz .LBB0_752
	s_mov_b64 s[8:9], exec
	s_waitcnt lgkmcnt(0)
	s_waitcnt vmcnt(0)
	v_mbcnt_lo_u32_b32 v1, s8, 0
	v_mbcnt_hi_u32_b32 v1, s9, v1
	v_cmp_eq_u32_e32 vcc, 0, v1
	s_and_saveexec_b64 s[10:11], vcc
	s_cbranch_execz .LBB0_737
	s_bcnt1_i32_b64 s8, s[8:9]
	v_mov_b32_e32 v2, 0xffc3000
	v_mov_b32_e32 v3, s8
	global_atomic_add v2, v2, v3, s[88:89] offset:1024 sc0
